# A1 first-half stream: K fragment prefill ds_reads issued first after the tile barrier (buffer select hoisted), scalar bookkeeping and P register moves after them
# speedup vs baseline: 1.0072x; 1.0072x over previous
; #define B_LOADK(Kb_, tile_) do { const char* kp_ = (const char*)(Kb_) + (size_t)(tile_) * (64 * LDK * 2); const unsigned ko_ = ((tile_) == NT - 1) ? koffL : koff; \
;     _Pragma("unroll") for (int i_ = 0; i_ < NKC; ++i_) rk[i_] = *(const u32x4*)(kp_ + ko_ + i_ * 128); } while (0)
; #define B_LOADV(Vb_, tile_) do { const char* vp_ = (const char*)(Vb_) + (size_t)(tile_) * 128; \
;     rv[0] = *(const u32x4*)(vp_ + voff); rv[1] = *(const u32x4*)(vp_ + voff + 64 * LP * 2); } while (0)
; template <int NHQ, int NHKV>
; DI void attn_phase_l1(const u16* __restrict__ Q, const u16* __restrict__ K, const u16* __restrict__ Vt, u16* __restrict__ O, const float* __restrict__ qg, char* smem, const int wv) {
;     ...
;     for (int j = 0; j < NT; ++j) {
;       if (j + 2 < NT) B_WRITEK(j & 1);
;       if (j + 1 < NT) B_WRITEV((j + 1) & 1);
;       __builtin_amdgcn_sched_barrier(0);
;       if (j + 3 < NT) B_LOADK(Kb, j + 3);
;       if (j + 2 < NT) B_LOADV(Vb, j + 2);
;       __builtin_amdgcn_sched_barrier(0);
;       if (j == NT - 1) {
;         const char* svl = vb0 + (j & 1) * VBYTES + r32 * VSTR + hh * 16;
;         bf16x8 vf[4];
; #pragma unroll
;         for (int d = 0; d < 4; ++d) vf[d] = *(const bf16x8*)(svl + d * 32 * VSTR);
; #pragma unroll
;         for (int d = 0; d < 4; ++d) o[d] = __builtin_amdgcn_mfma_f32_32x32x16_bf16(vf[d], pb[0], o[d], 0, 0, 0);
;       } else {
;         constexpr int NQK = 2 * NS, NM = NQK + 16, RING = 8;
;         const char* sk = kb0 + ((j + 1) & 1) * KBYTES + r32 * KSTR + hh * 16;
;         const char* sv = vb0 + (j & 1) * VBYTES + r32 * VSTR + hh * 16;
;         bf16x8 ring[RING];
;         unsigned w_[16]; f32x2 ps2 = {0.f, 0.f};
;     ...
; #pragma unroll
;         for (int i = 0; i < 16; ++i) { s0[i] = 0.f; s1[i] = 0.f; }
; #pragma unroll
;         for (int i = 0; i < RING; ++i) B_FRAG(ring[i], i);
; #pragma unroll
;         for (int i = 0; i < NM; ++i) {
;           if (i < NQK) {
;             if (i & 1) s1 = __builtin_amdgcn_mfma_f32_32x32x16_bf16(ring[i % RING], qf[i >> 1], s1, 0, 0, 0);
;             else       s0 = __builtin_amdgcn_mfma_f32_32x32x16_bf16(ring[i % RING], qf[i >> 1], s0, 0, 0, 0);
;           } else {
;             o[(i - NQK) & 3] = __builtin_amdgcn_mfma_f32_32x32x16_bf16(ring[i % RING], pb[(i - NQK) >> 2], o[(i - NQK) & 3], 0, 0, 0);
;           }
;           if (i + RING < NM) B_FRAG(ring[i % RING], i + RING);
.LBB0_1217:
	s_bitcmp1_b32 s42, 0
	s_cselect_b32 s99, 0x4400, 0
	v_add_u32_e32 v164, s99, v205
	ds_read_b128 v[64:67], v164
	ds_read_b128 v[178:181], v164 offset:32
	ds_read_b128 v[182:185], v164 offset:8736
	ds_read_b128 v[186:189], v164 offset:8768
	ds_read_b128 v[190:193], v164 offset:64
	ds_read_b128 v[194:197], v164 offset:96
	ds_read_b128 v[214:217], v164 offset:8800
	s_add_i32 s27, s42, 1
	s_bitcmp1_b32 s27, 0
	s_cselect_b64 s[20:21], -1, 0
	s_and_b64 s[22:23], s[20:21], exec
	s_cselect_b32 s26, 0x4400, 0
	s_bitcmp1_b32 s42, 0
	s_cselect_b64 s[22:23], -1, 0
	s_and_b64 s[44:45], s[22:23], exec
	s_cselect_b32 s43, 0x4800, 0
	v_mov_b32_e32 v156, v92
	v_mov_b32_e32 v152, v88
	v_mov_b32_e32 v148, v84
	v_mov_b32_e32 v144, v80
	s_waitcnt lgkmcnt(6)
	v_mfma_f32_32x32x16_bf16 v[80:95], v[64:67], v[100:103], 0
	ds_read_b128 v[68:71], v164 offset:8704
	ds_read_b128 v[220:223], v164 offset:128
	s_and_b64 s[20:21], s[20:21], exec
	s_cselect_b32 s20, 0x4800, 0
	v_add_u32_e32 v177, s20, v206
	ds_read_b128 v[224:227], v164 offset:8832
	s_waitcnt lgkmcnt(2)
	v_mfma_f32_32x32x16_bf16 v[64:79], v[68:71], v[100:103], 0
	v_mfma_f32_32x32x16_bf16 v[80:95], v[178:181], v[108:111], v[80:95]
	ds_read_b128 v[228:231], v164 offset:160
	ds_read_b128 v[178:181], v164 offset:8864
	s_waitcnt vmcnt(0)
	v_add_u32_e32 v238, s26, v203
	ds_write_b128 v238, v[128:131]
	v_mfma_f32_32x32x16_bf16 v[64:79], v[182:185], v[108:111], v[64:79]
	ds_write_b128 v238, v[132:135] offset:128
	v_mfma_f32_32x32x16_bf16 v[80:95], v[190:193], v[96:99], v[80:95]
	ds_read_b128 v[182:185], v164 offset:192
	ds_read_b128 v[190:193], v164 offset:8896
	v_add_u32_e32 v239, s43, v204
	ds_write_b128 v239, v[136:139] offset:34816
	v_mfma_f32_32x32x16_bf16 v[64:79], v[186:189], v[96:99], v[64:79]
	ds_write_b128 v239, v[140:143] offset:44032
	v_mfma_f32_32x32x16_bf16 v[80:95], v[194:197], v[104:107], v[80:95]
	ds_read_b128 v[186:189], v164 offset:224
	ds_read_b128 v[194:197], v164 offset:8928
	s_cmp_gt_u32 s27, 61
	s_cbranch_scc1 .Lmy_a1_skipk
	s_cmp_eq_u32 s42, 60
	s_cselect_b64 vcc, -1, 0
	s_add_u32 s42, s6, s24
	v_cndmask_b32_e32 v242, v160, v201, vcc
	s_addc_u32 s43, s7, s25
	v_mov_b32_e32 v243, 0
	v_lshl_add_u64 v[240:241], s[42:43], 0, v[242:243]
	v_add_co_u32_e32 v240, vcc, 0x38b18000, v240
	s_nop 1
	v_addc_co_u32_e32 v241, vcc, 0, v241, vcc
	global_load_dwordx4 v[128:131], v[240:241], off
	global_load_dwordx4 v[132:135], v[240:241], off offset:128

; __global__ void __launch_bounds__(NTHREADS) fwd_megakernel(Params Punused) {
;   extern __shared__ __attribute__((aligned(16))) char smem[];
	.amdhsa_kernel _Z14fwd_megakernel6Params
		.amdhsa_group_segment_fixed_size 0
		.amdhsa_private_segment_fixed_size 0
		.amdhsa_kernarg_size 448
		.amdhsa_user_sgpr_count 2
		.amdhsa_user_sgpr_dispatch_ptr 0
		.amdhsa_user_sgpr_queue_ptr 0
		.amdhsa_user_sgpr_kernarg_segment_ptr 1
		.amdhsa_user_sgpr_dispatch_id 0
		.amdhsa_user_sgpr_kernarg_preload_length 0
		.amdhsa_user_sgpr_kernarg_preload_offset 0
		.amdhsa_user_sgpr_private_segment_size 0
		.amdhsa_uses_dynamic_stack 0
		.amdhsa_enable_private_segment 0
		.amdhsa_system_sgpr_workgroup_id_x 1
		.amdhsa_system_sgpr_workgroup_id_y 0
		.amdhsa_system_sgpr_workgroup_id_z 0
		.amdhsa_system_sgpr_workgroup_info 0
		.amdhsa_system_vgpr_workitem_id 2
		.amdhsa_next_free_vgpr 256
		.amdhsa_next_free_sgpr 100
		.amdhsa_accum_offset 256
		.amdhsa_reserve_vcc 1
		.amdhsa_float_round_mode_32 0
		.amdhsa_float_round_mode_16_64 0
		.amdhsa_float_denorm_mode_32 3
		.amdhsa_float_denorm_mode_16_64 3
		.amdhsa_dx10_clamp 1
		.amdhsa_ieee_mode 1
		.amdhsa_fp16_overflow 0
		.amdhsa_tg_split 0
		.amdhsa_exception_fp_ieee_invalid_op 0
		.amdhsa_exception_fp_denorm_src 0
		.amdhsa_exception_fp_ieee_div_zero 0
		.amdhsa_exception_fp_ieee_overflow 0
		.amdhsa_exception_fp_ieee_underflow 0
		.amdhsa_exception_fp_ieee_inexact 0
		.amdhsa_exception_int_div_zero 0
	.end_amdhsa_kernel

; __global__ void __launch_bounds__(NTHREADS) fwd_megakernel(Params Punused) {
;   extern __shared__ __attribute__((aligned(16))) char smem[];
amdhsa.kernels:
  - .agpr_count:     0
    .args:
      - .offset:         0
        .size:           192
        .value_kind:     by_value
      - .offset:         192
        .size:           4
        .value_kind:     hidden_block_count_x
      - .offset:         196
        .size:           4
        .value_kind:     hidden_block_count_y
      - .offset:         200
        .size:           4
        .value_kind:     hidden_block_count_z
      - .offset:         204
        .size:           2
        .value_kind:     hidden_group_size_x
      - .offset:         206
        .size:           2
        .value_kind:     hidden_group_size_y
      - .offset:         208
        .size:           2
        .value_kind:     hidden_group_size_z
      - .offset:         210
        .size:           2
        .value_kind:     hidden_remainder_x
      - .offset:         212
        .size:           2
        .value_kind:     hidden_remainder_y
      - .offset:         214
        .size:           2
        .value_kind:     hidden_remainder_z
      - .offset:         232
        .size:           8
        .value_kind:     hidden_global_offset_x
      - .offset:         240
        .size:           8
        .value_kind:     hidden_global_offset_y
      - .offset:         248
        .size:           8
        .value_kind:     hidden_global_offset_z
      - .offset:         256
        .size:           2
        .value_kind:     hidden_grid_dims
      - .offset:         280
        .size:           8
        .value_kind:     hidden_multigrid_sync_arg
      - .offset:         312
        .size:           4
        .value_kind:     hidden_dynamic_lds_size
    .group_segment_fixed_size: 0
    .kernarg_segment_align: 8
    .kernarg_segment_size: 448
    .language:       OpenCL C
    .language_version:
      - 2
      - 0
    .max_flat_workgroup_size: 512
    .name:           _Z14fwd_megakernel6Params
    .private_segment_fixed_size: 0
    .sgpr_count:     106
    .sgpr_spill_count: 0
    .symbol:         _Z14fwd_megakernel6Params.kd
    .uniform_work_group_size: 1
    .uses_dynamic_stack: false
    .vgpr_count:     256
    .vgpr_spill_count: 0
    .wavefront_size: 64
